# one static s_setprio 1 for waves 4-7 while they run mixer units (reset at mixer exit)
# baseline (speedup 1.0000x reference)
.LBB0_960:
	s_or_b64 exec, exec, s[0:1]
	v_readfirstlane_b32 s58, v228
	s_lshr_b32 s58, s58, 8
	s_cmp_lg_u32 s58, 0
	s_cbranch_scc0 .Lmy_prio_skip
	s_setprio 1
.Lmy_prio_skip:
	s_mov_b64 s[0:1], s[80:81]
	s_mov_b32 s45, s74
	s_cmp_gt_i32 s86, 15
	s_mov_b64 s[6:7], -1
	s_cbranch_scc0 .LBB0_1822
	s_cmpk_gt_u32 s86, 0x10f
	s_cbranch_scc0 .LBB0_1541
	s_cmpk_gt_u32 s86, 0x18f
	s_cbranch_scc0 .LBB0_1260
	s_cmpk_gt_u32 s86, 0x28f
	s_cbranch_scc0 .LBB0_1199
	s_cmpk_gt_u32 s86, 0x38f
	s_cbranch_scc0 .LBB0_1145
	s_cmpk_gt_u32 s86, 0x48f
	s_cbranch_scc0 .LBB0_1078
	s_cmpk_gt_u32 s86, 0x50f
	s_cbranch_scc0 .LBB0_1053
	s_cmpk_gt_u32 s86, 0x58f
	s_cbranch_scc0 .LBB0_1046
	s_cmpk_gt_u32 s86, 0x5cf
	s_cbranch_scc0 .LBB0_1036
	s_cmpk_gt_u32 s86, 0x6cf
	s_cbranch_scc0 .LBB0_1018
	s_cmpk_gt_u32 s86, 0x74f
	s_cbranch_scc0 .LBB0_1004
	s_and_saveexec_b64 s[6:7], s[26:27]
	s_cbranch_execz .LBB0_984
	global_load_dword v0, v65, s[70:71] offset:2304 sc1
	s_waitcnt vmcnt(0)
	v_cmp_lt_u32_e32 vcc, 15, v0
	s_cbranch_vccnz .LBB0_983
	s_mov_b32 s10, 0x3ffff8
	s_branch .LBB0_975

.LBB0_1838:
	s_setprio 0
	v_readlane_b32 s71, v254, 12
	s_mov_b32 s6, s71
	s_waitcnt vmcnt(0)
	s_barrier
	s_and_saveexec_b64 s[0:1], s[26:27]
	s_cbranch_execz .LBB0_1875
	v_readlane_b32 s7, v255, 17
	s_waitcnt vmcnt(0) expcnt(0) lgkmcnt(0)
	s_mov_b64 s[4:5], exec
	v_mov_b32_e32 v0, s7
	v_readlane_b32 s7, v255, 18
	ds_read_b32 v2, v0
	v_mbcnt_lo_u32_b32 v1, s4, 0
	v_mov_b32_e32 v0, s7
	ds_read_b32 v0, v0
	v_mbcnt_hi_u32_b32 v1, s5, v1
	s_lshl_b32 s20, s6, 6
	v_cmp_eq_u32_e32 vcc, 0, v1
	s_and_saveexec_b64 s[6:7], vcc
	s_cbranch_execz .LBB0_1841
	s_add_i32 s96, s20, 0x500
	s_lshr_b32 s9, s20, 1
	s_add_i32 s9, s9, 0xe50
	v_readlane_b32 s8, v255, 46
	s_cmp_lg_u32 s8, 0
	s_cselect_b32 s96, s9, s96
	s_lshl_b64 s[8:9], s[96:97], 2
	v_readlane_b32 s10, v254, 10
	v_readlane_b32 s11, v254, 11
	s_add_u32 s8, s10, s8
	s_addc_u32 s9, s11, s9
	s_bcnt1_i32_b64 s4, s[4:5]
	v_mov_b32_e32 v3, s4
	global_atomic_add v3, v65, v3, s[8:9] sc0
